# grid barrier: followers poll the global generation word directly instead of the per-XCD republished word (one hop less)
# baseline (speedup 1.0000x reference)
; __device__ __forceinline__ unsigned xb_ld(unsigned* p)              { return __hip_atomic_load(p, __ATOMIC_RELAXED, __HIP_MEMORY_SCOPE_AGENT); }
; __device__ __forceinline__ unsigned xb_add(unsigned* p, unsigned v) { return __hip_atomic_fetch_add(p, v, __ATOMIC_RELAXED, __HIP_MEMORY_SCOPE_AGENT); }
; #define XB_SPIN(cond, bar) do { unsigned _sp = 0; while (cond) { __builtin_amdgcn_s_sleep(1); \
;     if ((++_sp & 255u) == 0u) { if (xb_ld(&(bar)[XB_TMO])) break; if (_sp > XB_SPIN_CAP) { atomicAdd(&(bar)[XB_TMO], 1u); break; } } } } while (0)
; __device__ __forceinline__ void xcd_barrier(unsigned* bar, volatile LAS unsigned* st, const int tid) {
;     ...
;         const unsigned old = xb_add(&bar[XB_XSUB(x)], 1u);
;         const unsigned gen = old / nloc;
;         if (old + 1u == (gen + 1u) * nloc) {
;             __builtin_amdgcn_fence(__ATOMIC_RELEASE, "agent");
;             asm volatile("s_waitcnt vmcnt(0)" ::: "memory");
;             const unsigned og = xb_add(&bar[XB_TOP], 1u);
;             const unsigned tg = og / nx;
;             if (og + 1u == (tg + 1u) * nx) xb_add(&bar[XB_TOPGEN], 1u);
;             else XB_SPIN(xb_ld(&bar[XB_TOPGEN]) == tg, bar);
;             __builtin_amdgcn_fence(__ATOMIC_ACQUIRE, "agent");
;             xb_add(&bar[XB_XGEN(x)], 1u);
;             asm volatile("s_waitcnt vmcnt(0)" ::: "memory");
;         } else {
;             XB_SPIN(xb_ld(&bar[XB_XGEN(x)]) == gen, bar);
;             __builtin_amdgcn_fence(__ATOMIC_ACQUIRE, "agent");
;             asm volatile("s_waitcnt vmcnt(0)" ::: "memory");
.LBB0_68:
	s_or_b64 exec, exec, s[24:25]
	v_cvt_f32_u32_e32 v4, v2
	s_waitcnt vmcnt(0)
	v_readfirstlane_b32 s3, v3
	v_sub_u32_e32 v3, 0, v2
	v_rcp_iflag_f32_e32 v4, v4
	v_add_u32_e32 v5, s3, v1
	v_mul_f32_e32 v4, 0x4f7ffffe, v4
	v_cvt_u32_f32_e32 v4, v4
	v_mul_lo_u32 v1, v3, v4
	v_mul_hi_u32 v1, v4, v1
	v_add_u32_e32 v1, v4, v1
	v_mul_hi_u32 v1, v5, v1
	v_mul_lo_u32 v3, v1, v2
	v_sub_u32_e32 v3, v5, v3
	v_add_u32_e32 v4, 1, v1
	v_cmp_ge_u32_e32 vcc, v3, v2
	s_nop 1
	v_cndmask_b32_e32 v1, v1, v4, vcc
	v_sub_u32_e32 v4, v3, v2
	v_cndmask_b32_e32 v3, v3, v4, vcc
	v_add_u32_e32 v4, 1, v1
	v_cmp_ge_u32_e32 vcc, v3, v2
	v_add_u32_e32 v3, 1, v5
	s_nop 0
	v_cndmask_b32_e32 v1, v1, v4, vcc
	v_mul_lo_u32 v4, v2, v1
	v_add_u32_e32 v2, v4, v2
	v_cmp_ne_u32_e32 vcc, v3, v2
	s_and_saveexec_b64 s[22:23], vcc
	s_xor_b64 s[22:23], exec, s[22:23]
	s_cbranch_execz .LBB0_82
	s_add_u32 s40, s54, 0x16e03500
	s_addc_u32 s41, s55, 0
	global_load_dword v0, v97, s[40:41] sc1
	s_waitcnt vmcnt(0)
	v_cmp_eq_u32_e32 vcc, v0, v1
	s_and_saveexec_b64 s[30:31], vcc
	s_cbranch_execz .LBB0_81
	s_mov_b32 s3, 1
	s_mov_b64 s[42:43], 0
	s_branch .LBB0_72
